# converted bf16 weight stores issued write-through (sc1)
# baseline (speedup 1.0000x reference)
.LBB0_61:
	s_lshl_b64 s[46:47], s[48:49], 1
	s_add_u32 s42, s42, s46
	s_addc_u32 s43, s43, s47
	v_lshl_add_u64 v[10:11], s[42:43], 0, v[8:9]
	v_cmp_gt_i32_e32 vcc, s10, v22
	s_and_saveexec_b64 s[42:43], vcc
	s_cbranch_execz .LBB0_63
	v_ashrrev_i32_e32 v22, 31, v23
	v_mul_lo_u32 v24, s39, v23
	v_mul_lo_u32 v25, s38, v22
	v_mad_u64_u32 v[22:23], s[46:47], s38, v23, 0
	v_add3_u32 v23, v23, v25, v24
	v_lshl_add_u64 v[22:23], v[22:23], 1, v[10:11]
	s_waitcnt lgkmcnt(0)
	global_store_dwordx4 v[22:23], v[0:3], off sc1

.LBB0_65:
	v_cmp_gt_i32_e32 vcc, s10, v23
	s_and_saveexec_b64 s[42:43], vcc
	s_cbranch_execz .LBB0_67
	v_ashrrev_i32_e32 v23, 31, v22
	v_mul_lo_u32 v24, s39, v22
	v_mul_lo_u32 v25, s38, v23
	v_mad_u64_u32 v[22:23], s[46:47], s38, v22, 0
	v_add3_u32 v23, v23, v25, v24
	v_lshl_add_u64 v[22:23], v[22:23], 1, v[10:11]
	s_waitcnt lgkmcnt(0)
	global_store_dwordx4 v[22:23], v[0:3], off sc1

.LBB0_89:
	v_cmp_gt_i32_e32 vcc, s10, v23
	s_and_saveexec_b64 s[4:5], vcc
	s_cbranch_execz .LBB0_45
	v_ashrrev_i32_e32 v23, 31, v22
	v_mul_lo_u32 v24, s39, v22
	v_mul_lo_u32 v25, s38, v23
	v_mad_u64_u32 v[22:23], s[38:39], s38, v22, 0
	v_add3_u32 v23, v23, v25, v24
	v_lshl_add_u64 v[10:11], v[22:23], 1, v[10:11]
	s_waitcnt lgkmcnt(0)
	global_store_dwordx4 v[10:11], v[0:3], off sc1
	s_branch .LBB0_45

.LBB0_528:
	s_lshl_b64 s[60:61], s[96:97], 1
	s_add_u32 s60, s70, s60
	s_addc_u32 s61, s71, s61
	v_lshl_add_u64 v[10:11], s[60:61], 0, v[0:1]
	v_cmp_gt_i32_e32 vcc, s46, v12
	s_and_saveexec_b64 s[60:61], vcc
	s_cbranch_execz .LBB0_530
	v_ashrrev_i32_e32 v12, 31, v13
	v_mul_lo_u32 v24, s69, v13
	v_mul_lo_u32 v25, s68, v12
	v_mad_u64_u32 v[12:13], s[70:71], s68, v13, 0
	v_add3_u32 v13, v13, v25, v24
	v_lshl_add_u64 v[12:13], v[12:13], 1, v[10:11]
	s_waitcnt lgkmcnt(0)
	global_store_dwordx4 v[12:13], v[2:5], off sc1

.LBB0_535:
	v_cmp_gt_i32_e32 vcc, s46, v12
	s_and_saveexec_b64 s[60:61], vcc
	s_cbranch_execz .LBB0_537
	v_ashrrev_i32_e32 v12, 31, v13
	v_mul_lo_u32 v24, s69, v13
	v_mul_lo_u32 v25, s68, v12
	v_mad_u64_u32 v[12:13], s[70:71], s68, v13, 0
	v_add3_u32 v13, v13, v25, v24
	v_lshl_add_u64 v[12:13], v[12:13], 1, v[10:11]
	s_waitcnt lgkmcnt(0)
	global_store_dwordx4 v[12:13], v[2:5], off sc1

.LBB0_852:
	s_lshl_b64 s[66:67], s[88:89], 1
	s_add_u32 s66, s68, s66
	s_addc_u32 s67, s69, s67
	v_lshl_add_u64 v[6:7], s[66:67], 0, v[0:1]
	v_cmp_gt_i32_e32 vcc, s46, v18
	s_and_saveexec_b64 s[68:69], vcc
	s_cbranch_execz .LBB0_854
	v_ashrrev_i32_e32 v18, 31, v19
	v_mul_lo_u32 v20, s63, v19
	v_mul_lo_u32 v21, s62, v18
	v_mad_u64_u32 v[18:19], s[66:67], s62, v19, 0
	v_add3_u32 v19, v19, v21, v20
	v_lshl_add_u64 v[18:19], v[18:19], 1, v[6:7]
	s_waitcnt lgkmcnt(0)
	global_store_dwordx4 v[18:19], v[2:5], off sc1

.LBB0_859:
	v_cmp_gt_i32_e32 vcc, s46, v18
	s_and_saveexec_b64 s[68:69], vcc
	s_cbranch_execz .LBB0_861
	v_ashrrev_i32_e32 v18, 31, v19
	v_mul_lo_u32 v20, s63, v19
	v_mul_lo_u32 v21, s62, v18
	v_mad_u64_u32 v[18:19], s[66:67], s62, v19, 0
	v_add3_u32 v19, v19, v21, v20
	v_lshl_add_u64 v[18:19], v[18:19], 1, v[6:7]
	s_waitcnt lgkmcnt(0)
	global_store_dwordx4 v[18:19], v[2:5], off sc1
